# P3 loop: per-tile bias scalars also computed in the previous tail; p0 QK chain is four back-to-back MFMAs
# baseline (speedup 1.0000x reference)
.LBB0_323:
	s_and_b32 s1, s79, 0x18000
	s_xor_b32 s0, s1, 0x10000
	v_add_u32_e32 v85, s0, v222
	v_add_u32_e32 v86, s0, v223
	v_add_u32_e32 v87, s0, v241
	v_add_u32_e32 v84, s0, v242
	v_cvt_f32_i32_e32 v156, s100
	v_fma_f32 v254, v208, v156, -v207
	v_add_f32_e32 v255, v237, v254
.Lk_top:
	ds_read_b128 v[80:83], v85 offset:16384
	ds_read_b128 v[202:205], v86 offset:16384
	ds_read_b128 v[194:197], v87 offset:16384
	ds_read_b128 v[186:189], v84 offset:16384
	ds_read_b128 v[198:201], v85 offset:20480
	ds_read_b128 v[190:193], v86 offset:20480
	ds_read_b128 v[246:249], v87 offset:20480
	ds_read_b128 v[250:253], v84 offset:20480
	s_cmp_ge_i32 s72, s98
	s_cbranch_scc1 .LBB0_325
	s_add_i32 m0, s1, s94
	s_add_i32 s4, s90, s1
	global_load_lds_dwordx4 v[220:221], off
	s_mov_b32 m0, s4
	s_add_i32 s4, s1, s66
	global_load_lds_dwordx4 v[218:219], off
	s_mov_b32 m0, s4
	global_load_lds_dwordx4 v[224:225], off
	global_load_lds_dwordx4 v[224:225], off offset:1024
.LBB0_325:
	s_waitcnt lgkmcnt(0)
	v_mfma_f32_32x32x16_bf16 v[96:111], v[80:83], v[144:147], v[64:79]
	v_mfma_f32_32x32x16_bf16 v[96:111], v[202:205], v[140:143], v[96:111]
	v_mfma_f32_32x32x16_bf16 v[96:111], v[194:197], v[136:139], v[96:111]
	v_mfma_f32_32x32x16_bf16 v[96:111], v[186:189], v[132:135], v[96:111]
	s_add_i32 s3, s79, 0xfffe8000
	s_and_b32 s3, s3, 0x18000
	v_add_u32_e32 v158, s3, v235
	v_add_u32_e32 v159, s3, v239
	v_add_u32_e32 v160, s3, v236
	v_add_u32_e32 v161, s3, v234
	ds_read_b64_tr_b16 v[182:183], v158 offset:32768
	ds_read_b64_tr_b16 v[184:185], v158 offset:34816
	ds_read_b64_tr_b16 v[178:179], v159 offset:32768
	ds_read_b64_tr_b16 v[180:181], v159 offset:34816
	ds_read_b64_tr_b16 v[148:149], v160 offset:32768
	ds_read_b64_tr_b16 v[150:151], v160 offset:34816
	ds_read_b64_tr_b16 v[152:153], v161 offset:32768
	ds_read_b64_tr_b16 v[154:155], v161 offset:34816
	v_mfma_f32_32x32x16_bf16 v[80:95], v[198:201], v[144:147], v[64:79]
	v_add_f32_e32 v96, v254, v96
	v_exp_f32_e32 v96, v96
	v_add_f32_e32 v97, v254, v97
	v_exp_f32_e32 v97, v97
	v_add_f32_e32 v98, v254, v98
	v_exp_f32_e32 v98, v98
	v_add_f32_e32 v99, v254, v99
	v_exp_f32_e32 v99, v99
	v_mfma_f32_32x32x16_bf16 v[80:95], v[190:193], v[140:143], v[80:95]
	v_add_f32_e32 v100, v254, v100
	v_exp_f32_e32 v100, v100
	v_add_f32_e32 v101, v254, v101
	v_exp_f32_e32 v101, v101
	v_add_f32_e32 v102, v254, v102
	v_exp_f32_e32 v102, v102
	v_add_f32_e32 v103, v254, v103
	v_exp_f32_e32 v103, v103
	v_mfma_f32_32x32x16_bf16 v[80:95], v[246:249], v[136:139], v[80:95]
	v_add_f32_e32 v104, v254, v104
	v_exp_f32_e32 v104, v104
	v_add_f32_e32 v105, v254, v105
	v_exp_f32_e32 v105, v105
	v_add_f32_e32 v106, v254, v106
	v_exp_f32_e32 v106, v106
	v_add_f32_e32 v107, v254, v107
	v_exp_f32_e32 v107, v107
	v_mfma_f32_32x32x16_bf16 v[80:95], v[250:253], v[132:135], v[80:95]
	v_add_f32_e32 v108, v254, v108
	v_exp_f32_e32 v108, v108
	v_add_f32_e32 v109, v254, v109
	v_exp_f32_e32 v109, v109
	v_add_f32_e32 v110, v254, v110
	v_exp_f32_e32 v110, v110
	v_add_f32_e32 v111, v254, v111
	v_exp_f32_e32 v111, v111
	s_cmp_le_i32 s72, s101
	s_cbranch_scc0 .Lmask_blk
.LBB0_327:
	s_waitcnt lgkmcnt(4)
	v_mfma_f32_32x32x16_bf16 v[48:63], v[182:185], v[174:177], v[48:63]
	v_add_f32_e32 v190, v255, v80
	v_exp_f32_e32 v190, v190
	ds_read_b64_tr_b16 v[246:247], v158 offset:36864
	ds_read_b64_tr_b16 v[248:249], v158 offset:38912
	v_add_f32_e32 v157, v190, v96
	v_mfma_f32_32x32x16_bf16 v[32:47], v[178:181], v[174:177], v[32:47]
	v_add_f32_e32 v191, v255, v81
	v_exp_f32_e32 v191, v191
	ds_read_b64_tr_b16 v[250:251], v159 offset:36864
	ds_read_b64_tr_b16 v[252:253], v159 offset:38912
	v_add_f32_e32 v156, v191, v97
	v_add_f32_e32 v157, v156, v157
	s_waitcnt lgkmcnt(4)
	v_mfma_f32_32x32x16_bf16 v[16:31], v[148:151], v[174:177], v[16:31]
	v_add_f32_e32 v192, v255, v82
	v_exp_f32_e32 v192, v192
	ds_read_b64_tr_b16 v[182:183], v160 offset:36864
	ds_read_b64_tr_b16 v[184:185], v160 offset:38912
	v_add_f32_e32 v156, v192, v98
	v_add_f32_e32 v157, v156, v157
	v_mfma_f32_32x32x16_bf16 v[0:15], v[152:155], v[174:177], v[0:15]
	v_add_f32_e32 v193, v255, v83
	v_exp_f32_e32 v193, v193
	ds_read_b64_tr_b16 v[178:179], v161 offset:36864
	ds_read_b64_tr_b16 v[180:181], v161 offset:38912
	v_add_f32_e32 v156, v193, v99
	v_add_f32_e32 v157, v156, v157
	v_cvt_pk_bf16_f32 v174, v96, v97
	s_waitcnt lgkmcnt(4)
	v_mfma_f32_32x32x16_bf16 v[48:63], v[246:249], v[162:165], v[48:63]
	v_add_f32_e32 v194, v255, v84
	v_exp_f32_e32 v194, v194
	ds_read_b64_tr_b16 v[148:149], v158 offset:40960
	ds_read_b64_tr_b16 v[150:151], v158 offset:43008
	v_add_f32_e32 v156, v194, v100
	v_add_f32_e32 v157, v156, v157
	v_cvt_pk_bf16_f32 v175, v98, v99
	v_mfma_f32_32x32x16_bf16 v[32:47], v[250:253], v[162:165], v[32:47]
	v_add_f32_e32 v195, v255, v85
	v_exp_f32_e32 v195, v195
	ds_read_b64_tr_b16 v[152:153], v159 offset:40960
	ds_read_b64_tr_b16 v[154:155], v159 offset:43008
	v_add_f32_e32 v156, v195, v101
	v_add_f32_e32 v157, v156, v157
	v_cvt_pk_bf16_f32 v176, v100, v101
	s_waitcnt lgkmcnt(4)
	v_mfma_f32_32x32x16_bf16 v[16:31], v[182:185], v[162:165], v[16:31]
	v_add_f32_e32 v196, v255, v86
	v_exp_f32_e32 v196, v196
	ds_read_b64_tr_b16 v[246:247], v160 offset:40960
	ds_read_b64_tr_b16 v[248:249], v160 offset:43008
	v_add_f32_e32 v156, v196, v102
	v_add_f32_e32 v157, v156, v157
	v_cvt_pk_bf16_f32 v177, v102, v103
	v_mfma_f32_32x32x16_bf16 v[0:15], v[178:181], v[162:165], v[0:15]
	v_add_f32_e32 v197, v255, v87
	v_exp_f32_e32 v197, v197
	ds_read_b64_tr_b16 v[250:251], v161 offset:40960
	ds_read_b64_tr_b16 v[252:253], v161 offset:43008
	v_add_f32_e32 v156, v197, v103
	v_add_f32_e32 v157, v156, v157
	v_cvt_pk_bf16_f32 v162, v104, v105
	s_waitcnt lgkmcnt(4)
	v_mfma_f32_32x32x16_bf16 v[48:63], v[148:151], v[170:173], v[48:63]
	v_add_f32_e32 v198, v255, v88
	v_exp_f32_e32 v198, v198
	ds_read_b64_tr_b16 v[182:183], v158 offset:45056
	ds_read_b64_tr_b16 v[184:185], v158 offset:47104
	v_add_f32_e32 v156, v198, v104
	v_add_f32_e32 v157, v156, v157
	v_cvt_pk_bf16_f32 v163, v106, v107
	v_mfma_f32_32x32x16_bf16 v[32:47], v[152:155], v[170:173], v[32:47]
	v_add_f32_e32 v199, v255, v89
	v_exp_f32_e32 v199, v199
	ds_read_b64_tr_b16 v[178:179], v159 offset:45056
	ds_read_b64_tr_b16 v[180:181], v159 offset:47104
	v_add_f32_e32 v156, v199, v105
	v_add_f32_e32 v157, v156, v157
	v_cvt_pk_bf16_f32 v164, v108, v109
	s_waitcnt lgkmcnt(4)
	v_mfma_f32_32x32x16_bf16 v[16:31], v[246:249], v[170:173], v[16:31]
	v_add_f32_e32 v200, v255, v90
	v_exp_f32_e32 v200, v200
	ds_read_b64_tr_b16 v[148:149], v160 offset:45056
	ds_read_b64_tr_b16 v[150:151], v160 offset:47104
	v_add_f32_e32 v156, v200, v106
	v_add_f32_e32 v157, v156, v157
	v_cvt_pk_bf16_f32 v165, v110, v111
	v_mfma_f32_32x32x16_bf16 v[0:15], v[250:253], v[170:173], v[0:15]
	v_add_f32_e32 v201, v255, v91
	v_exp_f32_e32 v201, v201
	ds_read_b64_tr_b16 v[152:153], v161 offset:45056
	ds_read_b64_tr_b16 v[154:155], v161 offset:47104
	v_add_f32_e32 v156, v201, v107
	v_add_f32_e32 v157, v156, v157
	v_cvt_pk_bf16_f32 v170, v190, v191
	s_waitcnt lgkmcnt(4)
	v_mfma_f32_32x32x16_bf16 v[48:63], v[182:185], v[166:169], v[48:63]
	v_add_f32_e32 v202, v255, v92
	v_exp_f32_e32 v202, v202
	v_cvt_pk_bf16_f32 v171, v192, v193
	v_add_f32_e32 v156, v202, v108
	v_add_f32_e32 v157, v156, v157
	v_mfma_f32_32x32x16_bf16 v[32:47], v[178:181], v[166:169], v[32:47]
	v_add_f32_e32 v203, v255, v93
	v_exp_f32_e32 v203, v203
	v_cvt_pk_bf16_f32 v172, v194, v195
	v_add_f32_e32 v156, v203, v109
	v_add_f32_e32 v157, v156, v157
	s_waitcnt lgkmcnt(0)
	v_mfma_f32_32x32x16_bf16 v[16:31], v[148:151], v[166:169], v[16:31]
	v_add_f32_e32 v204, v255, v94
	v_exp_f32_e32 v204, v204
	v_cvt_pk_bf16_f32 v173, v196, v197
	v_add_f32_e32 v156, v204, v110
	v_add_f32_e32 v157, v156, v157
	v_mfma_f32_32x32x16_bf16 v[0:15], v[152:155], v[166:169], v[0:15]
	v_add_f32_e32 v205, v255, v95
	v_exp_f32_e32 v205, v205
	v_cvt_pk_bf16_f32 v166, v198, v199
	v_add_f32_e32 v156, v205, v111
	v_add_f32_e32 v157, v156, v157
	v_cvt_pk_bf16_f32 v167, v200, v201
	v_cvt_pk_bf16_f32 v168, v202, v203
	v_cvt_pk_bf16_f32 v169, v204, v205
	s_add_i32 s72, s72, 1
	s_add_i32 s79, s79, 0x8000
	s_add_i32 s100, s100, 64
	v_add_f32_e32 v229, v229, v157
	v_lshl_add_u64 v[218:219], v[218:219], 0, s[88:89]
	v_lshl_add_u64 v[220:221], v[220:221], 0, s[88:89]
	v_lshl_add_u64 v[224:225], v[224:225], 0, s[92:93]
	s_and_b32 s1, s79, 0x18000
	s_xor_b32 s0, s1, 0x10000
	v_add_u32_e32 v85, s0, v222
	v_add_u32_e32 v86, s0, v223
	v_add_u32_e32 v87, s0, v241
	v_add_u32_e32 v84, s0, v242
	v_cvt_f32_i32_e32 v156, s100
	v_fma_f32 v254, v208, v156, -v207
	v_add_f32_e32 v255, v237, v254
	s_cmp_ge_i32 s72, s99
	s_cbranch_scc1 .LBB0_332
	s_cmp_ge_i32 s72, s73
	s_cbranch_scc1 .Lk_last
	s_waitcnt vmcnt(4) lgkmcnt(0)
	s_barrier
	s_branch .Lk_top
